# P14: next_unit producer moved to wave 4 with the lagging half's re-stagger barrier placed after next_unit
# baseline (speedup 1.0000x reference)
; __device__ __forceinline__ void next_unit(const Call& C, int i, int& pm, int& pn, int& kp0, int& np, int& slice) {
;     const long L = (long)i * C.G + C.c;
;     const int nM = C.j0.nM, nN = C.j0.nN, nwg = nM * nN, P = C.K / (2 * BK);
;     const int S = C.j0.S, nsl = C.j0.cM * nN * S;
;     pm = -1; pn = 0; kp0 = 0; np = P; slice = -1;
;     if (L < nwg) {
; __device__ __forceinline__ void gemm_phase(LAS unsigned char* lds, const Call& C, const int tid, const Args& args) {
;     ...
;         next_unit(C, ui + 1, nxt.pm, nxt.pn, nxt.kp0, nxt.np, nxt.slice);
.LBB0_267:
	s_add_i32 s92, s92, 1
	s_cmp_eq_u32 s20, 0x1000
	s_cbranch_scc1 .Lnu_compute
	s_cmp_lt_u32 s16, 2
	s_cbranch_scc1 .Lnu_compute
	s_branch .LBB0_280

; #define PG8_STAGE(bufoff, gbase, voff) do { _Pragma("unroll") for (int _i = 0; _i < 2; ++_i) { unsigned _vo = (voff)[_i]; asm volatile("" : "+v"(_vo));   \
;         __builtin_amdgcn_global_load_lds((const unsigned*)((const char*)(gbase) + _vo), (LAS unsigned*)(lds + (bufoff) + ldsw + _i * 8192), 16, 0, 0); } } while (0)
; #define PG8_LDA(dst, b, h) do { _Pragma("unroll") for (int m = 0; m < 4; ++m) _Pragma("unroll") for (int k = 0; k < 2; ++k) dst[m][k] = *(const LAS bf16x8*)(lds + PG8_SA(b, h) + aoff + m * 2048 + k * 1024); } while (0)
; #define PG8_LDB(dst, b, h) do { _Pragma("unroll") for (int n = 0; n < 2; ++n) _Pragma("unroll") for (int k = 0; k < 2; ++k) dst[n][k] = *(const LAS bf16x8*)(lds + PG8_SB(b, h) + boff + n * 2048 + k * 1024); } while (0)
; #define PG8_MMA(ai, bj, At, Bt) do { __builtin_amdgcn_s_setprio(1); _Pragma("unroll") for (int m = 0; m < 4; ++m) _Pragma("unroll") for (int n = 0; n < 2; ++n) _Pragma("unroll") for (int k = 0; k < 2; ++k) \
;         acc[ai][bj][m][n] = __builtin_amdgcn_mfma_f32_16x16x32_bf16(Bt[n][k], At[m][k], acc[ai][bj][m][n], 0, 0, 0); __builtin_amdgcn_s_setprio(0); } while (0)
; #define PG8_WAIT_V(n) asm volatile("s_waitcnt vmcnt(" #n ")" ::: "memory")
; #define PG8_WAIT_L(n) asm volatile("s_waitcnt lgkmcnt(" #n ")" ::: "memory")
; #define PG8_BAR __builtin_amdgcn_s_barrier()
; #define PG8_SCHED __builtin_amdgcn_sched_barrier(0)
; __device__ __forceinline__ void gemm_phase(LAS unsigned char* lds, const Call& C, const int tid, const Args& args) {
;     ...
;         for (int t = 0; t < nt; t += 2) {
;             const bool last = (t == nt - 2);
;             const char* a1 = cA + (size_t)(t + 1) * kstep;
;             const char* a2 = last ? nA : cA + (size_t)(t + 2) * kstep; const char* b2 = last ? nB : cB + (size_t)(t + 2) * kstep;
;             const char* a3 = a2 + kstep; const char* b3 = b2 + kstep;
;             PG8_LDB(B0, 0, 0); PG8_LDB(B1, 0, 1); PG8_SCHED; PG8_LDA(At, 0, 0); PG8_STAGE(PG8_SA(1, 1), a1 + hstepA, voffA);
;             PG8_WAIT_V(8); PG8_WAIT_L(0); PG8_BAR; PG8_MMA(0, 0, At, B0); PG8_MMA(0, 1, At, B1); PG8_BAR; PG8_SCHED;
;     ...
;         if (wr == 1) PG8_BAR;
.LBB0_280:
	s_cmp_lg_u32 s20, 0x1000
	s_cbranch_scc1 .Lnu_noprod
	s_and_b32 vcc_lo, s92, 1
	s_lshl_b32 vcc_lo, vcc_lo, 6
	s_add_i32 vcc_lo, vcc_lo, 0x20200
	v_mov_b32_e32 v200, s91
	v_mov_b32_e32 v201, s54
	v_mov_b32_e32 v202, s95
	v_mov_b32_e32 v203, s5
	v_mov_b32_e32 v206, s48
	v_mov_b32_e32 v207, s49
	v_mov_b32_e32 v208, s86
	v_mov_b32_e32 v209, s87
	v_mov_b32_e32 v210, s36
	v_mov_b32_e32 v211, s37
	v_mov_b32_e32 v212, vcc_lo
	s_mov_b64 exec, 1
	ds_write_b128 v212, v[200:203]
	ds_write_b128 v212, v[206:209] offset:16
	ds_write_b64 v212, v[210:211] offset:32
	s_mov_b64 exec, -1
.Lnu_noprod:
	s_cmp_eq_u32 s16, 0
	s_cbranch_scc1 .LBB0_313
	s_lshl_b32 s12, s16, 1
	s_add_i32 s13, s12, -2
	s_add_u32 s16, s8, 0x100
	s_addc_u32 s17, s9, 0
	s_mov_b32 s24, 0
	s_waitcnt lgkmcnt(0)
	s_bitcmp1_b32 s101, 31
	s_cbranch_scc0 .Lbf2_nb
	s_bitset0_b32 s101, 31
	s_barrier
.Lbf2_nb:
	s_add_i32 s25, s24, 2
	s_add_u32 s8, s0, 0x100
	s_addc_u32 s9, s1, 0
	s_add_i32 s34, 0, 0x10000
	s_cmp_eq_u32 s13, s24
	s_cselect_b32 s39, s87, s9
	s_cselect_b32 s38, s86, s8
	v_add_u32_e32 v80, s34, v245
	s_cselect_b32 s41, s49, s17
	s_cselect_b32 s40, s48, s16
	s_add_i32 s24, 0, 0x14000
	ds_read_b128 v[136:139], v80
	ds_read_b128 v[140:143], v80 offset:1024
	ds_read_b128 v[144:147], v80 offset:2048
	ds_read_b128 v[148:151], v80 offset:3072
	v_add_u32_e32 v80, s24, v245
	ds_read_b128 v[152:155], v80
	ds_read_b128 v[156:159], v80 offset:1024
	ds_read_b128 v[160:163], v80 offset:2048
	ds_read_b128 v[164:167], v80 offset:3072
	v_mov_b32_e32 v80, v205
	s_add_u32 s0, s0, s89
	ds_read_b128 v[168:171], v246
	ds_read_b128 v[172:175], v246 offset:1024
	ds_read_b128 v[176:179], v246 offset:2048
	ds_read_b128 v[180:183], v246 offset:3072
	ds_read_b128 v[184:187], v246 offset:4096
	ds_read_b128 v[188:191], v246 offset:5120
	ds_read_b128 v[192:195], v246 offset:6144
	ds_read_b128 v[196:199], v246 offset:7168
	s_addc_u32 s1, s1, s94
	s_add_i32 m0, s20, 0xc000
	s_nop 0
	global_load_lds_dwordx4 v80, s[0:1]
	v_mov_b32_e32 v80, v243
	s_add_i32 m0, s20, 0xe000
	s_nop 0
	global_load_lds_dwordx4 v80, s[0:1]
	s_waitcnt vmcnt(8)
	s_waitcnt lgkmcnt(0)
	s_barrier
	s_setprio 1
	s_waitcnt lgkmcnt(0)
	v_mfma_f32_16x16x32_bf16 v[132:135], v[136:139], v[168:171], 0
	v_mfma_f32_16x16x32_bf16 v[128:131], v[144:147], v[168:171], 0
	v_mfma_f32_16x16x32_bf16 v[124:127], v[136:139], v[176:179], 0
	v_mfma_f32_16x16x32_bf16 v[120:123], v[144:147], v[176:179], 0
	v_mfma_f32_16x16x32_bf16 v[108:111], v[136:139], v[184:187], 0
	v_mfma_f32_16x16x32_bf16 v[104:107], v[144:147], v[184:187], 0
	v_mfma_f32_16x16x32_bf16 v[92:95], v[136:139], v[192:195], 0
	v_mfma_f32_16x16x32_bf16 v[86:89], v[144:147], v[192:195], 0
	v_mfma_f32_16x16x32_bf16 v[132:135], v[140:143], v[172:175], v[132:135]
	v_mfma_f32_16x16x32_bf16 v[128:131], v[148:151], v[172:175], v[128:131]
	v_mfma_f32_16x16x32_bf16 v[124:127], v[140:143], v[180:183], v[124:127]
	v_mfma_f32_16x16x32_bf16 v[120:123], v[148:151], v[180:183], v[120:123]
	v_mfma_f32_16x16x32_bf16 v[108:111], v[140:143], v[188:191], v[108:111]
	v_mfma_f32_16x16x32_bf16 v[104:107], v[148:151], v[188:191], v[104:107]
	v_mfma_f32_16x16x32_bf16 v[92:95], v[140:143], v[196:199], v[92:95]
	v_mfma_f32_16x16x32_bf16 v[86:89], v[148:151], v[196:199], v[86:89]
	s_setprio 0
	s_setprio 1
	v_mfma_f32_16x16x32_bf16 v[116:119], v[152:155], v[168:171], 0
	v_mfma_f32_16x16x32_bf16 v[112:115], v[160:163], v[168:171], 0
	v_mfma_f32_16x16x32_bf16 v[100:103], v[152:155], v[176:179], 0
	v_mfma_f32_16x16x32_bf16 v[96:99], v[160:163], v[176:179], 0
	v_mfma_f32_16x16x32_bf16 v[76:79], v[152:155], v[184:187], 0
	v_mfma_f32_16x16x32_bf16 v[72:75], v[160:163], v[184:187], 0
	v_mfma_f32_16x16x32_bf16 v[68:71], v[152:155], v[192:195], 0
	v_mfma_f32_16x16x32_bf16 v[60:63], v[160:163], v[192:195], 0
	v_mfma_f32_16x16x32_bf16 v[116:119], v[156:159], v[172:175], v[116:119]
	v_mfma_f32_16x16x32_bf16 v[112:115], v[164:167], v[172:175], v[112:115]
	v_mfma_f32_16x16x32_bf16 v[100:103], v[156:159], v[180:183], v[100:103]
	v_mfma_f32_16x16x32_bf16 v[96:99], v[164:167], v[180:183], v[96:99]
	v_mfma_f32_16x16x32_bf16 v[76:79], v[156:159], v[188:191], v[76:79]
	v_mfma_f32_16x16x32_bf16 v[72:75], v[164:167], v[188:191], v[72:75]
	v_mfma_f32_16x16x32_bf16 v[68:71], v[156:159], v[196:199], v[68:71]
	v_mfma_f32_16x16x32_bf16 v[60:63], v[164:167], v[196:199], v[60:63]
	s_setprio 0
	s_barrier
; #define PG8_STAGE(bufoff, gbase, voff) do { _Pragma("unroll") for (int _i = 0; _i < 2; ++_i) { unsigned _vo = (voff)[_i]; asm volatile("" : "+v"(_vo));   \
;         __builtin_amdgcn_global_load_lds((const unsigned*)((const char*)(gbase) + _vo), (LAS unsigned*)(lds + (bufoff) + ldsw + _i * 8192), 16, 0, 0); } } while (0)
; #define PG8_LDA(dst, b, h) do { _Pragma("unroll") for (int m = 0; m < 4; ++m) _Pragma("unroll") for (int k = 0; k < 2; ++k) dst[m][k] = *(const LAS bf16x8*)(lds + PG8_SA(b, h) + aoff + m * 2048 + k * 1024); } while (0)
; #define PG8_MMA(ai, bj, At, Bt) do { __builtin_amdgcn_s_setprio(1); _Pragma("unroll") for (int m = 0; m < 4; ++m) _Pragma("unroll") for (int n = 0; n < 2; ++n) _Pragma("unroll") for (int k = 0; k < 2; ++k) \
;         acc[ai][bj][m][n] = __builtin_amdgcn_mfma_f32_16x16x32_bf16(Bt[n][k], At[m][k], acc[ai][bj][m][n], 0, 0, 0); __builtin_amdgcn_s_setprio(0); } while (0)
; #define PG8_WAIT_V(n) asm volatile("s_waitcnt vmcnt(" #n ")" ::: "memory")
; #define PG8_WAIT_L(n) asm volatile("s_waitcnt lgkmcnt(" #n ")" ::: "memory")
; #define PG8_BAR __builtin_amdgcn_s_barrier()
; #define PG8_SCHED __builtin_amdgcn_sched_barrier(0)
; __device__ __forceinline__ void gemm_phase(LAS unsigned char* lds, const Call& C, const int tid, const Args& args) {
;     ...
;         next_unit(C, ui + 1, nxt.pm, nxt.pn, nxt.kp0, nxt.np, nxt.slice);
;     ...
;             PG8_LDA(At, 0, 1); PG8_STAGE(PG8_SB(0, 0), b2, voffB); PG8_STAGE(PG8_SB(0, 1), b2 + hstepB, voffB); PG8_STAGE(PG8_SA(0, 0), a2, voffA);
;             PG8_WAIT_V(8); PG8_WAIT_L(0); PG8_BAR; PG8_MMA(1, 0, At, B0); PG8_MMA(1, 1, At, B1); PG8_BAR; PG8_SCHED;
	v_mov_b32_e32 v80, v242
	s_add_i32 s0, s34, s23
	ds_read_b128 v[168:171], v246 offset:16384
	ds_read_b128 v[172:175], v246 offset:17408
	ds_read_b128 v[176:179], v246 offset:18432
	ds_read_b128 v[180:183], v246 offset:19456
	ds_read_b128 v[184:187], v246 offset:20480
	ds_read_b128 v[188:191], v246 offset:21504
	ds_read_b128 v[192:195], v246 offset:22528
	ds_read_b128 v[196:199], v246 offset:23552
	s_mov_b32 m0, s0
	s_nop 0
	global_load_lds_dwordx4 v80, s[40:41]
	v_mov_b32_e32 v80, v244
	s_add_i32 m0, s0, 0x2000
	s_add_u32 s0, s40, s74
	global_load_lds_dwordx4 v80, s[40:41]
	s_addc_u32 s1, s41, s75
	v_mov_b32_e32 v80, v242
	s_add_i32 s24, s24, s23
	s_mov_b32 m0, s24
	s_nop 0
	global_load_lds_dwordx4 v80, s[0:1]
	v_mov_b32_e32 v80, v244
	s_add_i32 m0, s24, 0x2000
	s_nop 0
	global_load_lds_dwordx4 v80, s[0:1]
	v_mov_b32_e32 v80, v205
	s_mov_b32 m0, s20
	s_nop 0
	global_load_lds_dwordx4 v80, s[38:39]
	v_mov_b32_e32 v80, v243
	s_mov_b32 m0, s72
	s_nop 0
	global_load_lds_dwordx4 v80, s[38:39]
	s_waitcnt vmcnt(8)
	s_waitcnt lgkmcnt(0)
	s_barrier
	s_setprio 1
	s_waitcnt lgkmcnt(0)
	v_mfma_f32_16x16x32_bf16 v[64:67], v[136:139], v[168:171], 0
	v_mfma_f32_16x16x32_bf16 v[56:59], v[144:147], v[168:171], 0
	v_mfma_f32_16x16x32_bf16 v[52:55], v[136:139], v[176:179], 0
	v_mfma_f32_16x16x32_bf16 v[48:51], v[144:147], v[176:179], 0
	v_mfma_f32_16x16x32_bf16 v[36:39], v[136:139], v[184:187], 0
	v_mfma_f32_16x16x32_bf16 v[32:35], v[144:147], v[184:187], 0
	v_mfma_f32_16x16x32_bf16 v[20:23], v[136:139], v[192:195], 0
	v_mfma_f32_16x16x32_bf16 v[16:19], v[144:147], v[192:195], 0
	v_mfma_f32_16x16x32_bf16 v[64:67], v[140:143], v[172:175], v[64:67]
	v_mfma_f32_16x16x32_bf16 v[56:59], v[148:151], v[172:175], v[56:59]
	v_mfma_f32_16x16x32_bf16 v[52:55], v[140:143], v[180:183], v[52:55]
	v_mfma_f32_16x16x32_bf16 v[48:51], v[148:151], v[180:183], v[48:51]
	v_mfma_f32_16x16x32_bf16 v[36:39], v[140:143], v[188:191], v[36:39]
	v_mfma_f32_16x16x32_bf16 v[32:35], v[148:151], v[188:191], v[32:35]
	v_mfma_f32_16x16x32_bf16 v[20:23], v[140:143], v[196:199], v[20:23]
	v_mfma_f32_16x16x32_bf16 v[16:19], v[148:151], v[196:199], v[16:19]
	s_setprio 0
	s_setprio 1
	v_mfma_f32_16x16x32_bf16 v[44:47], v[152:155], v[168:171], 0
	v_mfma_f32_16x16x32_bf16 v[40:43], v[160:163], v[168:171], 0
	v_mfma_f32_16x16x32_bf16 v[28:31], v[152:155], v[176:179], 0
	v_mfma_f32_16x16x32_bf16 v[24:27], v[160:163], v[176:179], 0
	v_mfma_f32_16x16x32_bf16 v[12:15], v[152:155], v[184:187], 0
	v_mfma_f32_16x16x32_bf16 v[8:11], v[160:163], v[184:187], 0
	v_mfma_f32_16x16x32_bf16 v[4:7], v[152:155], v[192:195], 0
	v_mfma_f32_16x16x32_bf16 v[0:3], v[160:163], v[192:195], 0
	v_mfma_f32_16x16x32_bf16 v[44:47], v[156:159], v[172:175], v[44:47]
	v_mfma_f32_16x16x32_bf16 v[40:43], v[164:167], v[172:175], v[40:43]
	v_mfma_f32_16x16x32_bf16 v[28:31], v[156:159], v[180:183], v[28:31]
	v_mfma_f32_16x16x32_bf16 v[24:27], v[164:167], v[180:183], v[24:27]
	v_mfma_f32_16x16x32_bf16 v[12:15], v[156:159], v[188:191], v[12:15]
	v_mfma_f32_16x16x32_bf16 v[8:11], v[164:167], v[188:191], v[8:11]
	v_mfma_f32_16x16x32_bf16 v[4:7], v[156:159], v[196:199], v[4:7]
	v_mfma_f32_16x16x32_bf16 v[0:3], v[164:167], v[196:199], v[0:3]
	s_setprio 0
	s_barrier
	s_branch .Lp7_ph3
.LBB0_282:
	s_cmp_lg_u32 s24, 2
	s_cbranch_scc1 .Lnu_nofetch
	s_cmp_eq_u32 s20, 0x1000
	s_cbranch_scc1 .Lnu_nofetch
	s_and_b32 vcc_lo, s92, 1
	s_lshl_b32 vcc_lo, vcc_lo, 6
	s_add_i32 vcc_lo, vcc_lo, 0x20200
	v_mov_b32_e32 v212, vcc_lo
	ds_read_b128 v[200:203], v212
	ds_read_b128 v[206:209], v212 offset:16
	ds_read_b64 v[210:211], v212 offset:32
	s_waitcnt lgkmcnt(0)
	v_readfirstlane_b32 s91, v200
	v_readfirstlane_b32 s54, v201
	v_readfirstlane_b32 s95, v202
	v_readfirstlane_b32 s5, v203
	v_readfirstlane_b32 s48, v206
	v_readfirstlane_b32 s49, v207
	v_readfirstlane_b32 s86, v208
	v_readfirstlane_b32 s87, v209
	v_readfirstlane_b32 s36, v210
	v_readfirstlane_b32 s37, v211
	s_nop 3

; #define PG8_BAR __builtin_amdgcn_s_barrier()
; __device__ __forceinline__ void gemm_phase(LAS unsigned char* lds, const Call& C, const int tid, const Args& args) {
;     ...
;         for (int t = 0; t < nt; t += 2) {
;     ...
;         if (wr == 1) PG8_BAR;
.LBB0_313:
	s_bitcmp1_b32 s101, 31
	s_cbranch_scc0 .Lbf2_nb2
	s_bitset0_b32 s101, 31
	s_barrier

; #define PG8_BAR __builtin_amdgcn_s_barrier()
; __device__ __forceinline__ void gemm_phase(LAS unsigned char* lds, const Call& C, const int tid, const Args& args) {
;     ...
;         epilogue(acc, C, cur, wr, wc, fr, fq, lane, wid, args, lds + PST_OFF);
;         if (!has_next) break;
; #pragma unroll
;         for (int a = 0; a < 2; ++a)
; #pragma unroll
;             for (int b = 0; b < 2; ++b)
; #pragma unroll
;                 for (int m = 0; m < 4; ++m)
; #pragma unroll
;                     for (int n = 0; n < 2; ++n) acc[a][b][m][n] = (f32x4){0.f, 0.f, 0.f, 0.f};
;         cur.pm = nxt.pm; cur.pn = nxt.pn; cur.kp0 = nxt.kp0; cur.np = nxt.np; cur.slice = nxt.slice; cA = nA; cB = nB; ++ui;
;         if (wr == 1) PG8_BAR;
.LBB0_496:
	v_readlane_b32 s0, v254, 57
	v_readlane_b32 s1, v254, 58
	s_andn2_b64 vcc, exec, s[0:1]
	s_cbranch_vccnz .LBB0_265
	s_bitset1_b32 s101, 31
	s_branch .LBB0_265
